# ConvGLU epilogue: removed 89 dead old-value initialisers before full-row DPP rotates
# baseline (speedup 1.0000x reference)
; #define LAS __attribute__((address_space(3)))
;     __device__ __forceinline__ void operator()(const pg8::f32x4 (&acc)[2][2][4][2], const pg8::Unit& u, int wr, int wc, int fr, int fq) const {
;     ...
;             for (int m = 0; m < 4; ++m) rsv[ai][m] = rsp[ai * 128 + m * 16];
; #pragma unroll
;         for (int ai = 0; ai < 2; ++ai)
; #pragma unroll
;             for (int m = 0; m < 4; ++m) rsv[ai][m] = rsqrtf(rsv[ai][m] * (1.0f / DM) + EPS);
;     ...
;         {
;             const f32x4 bg0 = *(const f32x4*)bpg, bg1 = *(const f32x4*)(bpg + 4);
; #pragma unroll
;             for (int ai = 0; ai < 2; ++ai) {
;                 const int gi = 2 * ai + wr;
;                 if (fr == 0)  { const float r_ = GLU_RS(ai, 0); *(LAS f32x4*)(xg + (gi * 2 + 0) * 128 + lf) = acc[ai][0][0][0] * r_ + bg0; *(LAS f32x4*)(xg + (gi * 2 + 0) * 128 + lf + 4) = acc[ai][0][0][1] * r_ + bg1; }
;                 if (fr == 15) { const float r_ = GLU_RS(ai, 3); *(LAS f32x4*)(xg + (gi * 2 + 1) * 128 + lf) = acc[ai][0][3][0] * r_ + bg0; *(LAS f32x4*)(xg + (gi * 2 + 1) * 128 + lf + 4) = acc[ai][0][3][1] * r_ + bg1; }
;             }
;             if (wr == 0 && fr < 2) {
;                 const float r_ = GLU_RS(0, 0);
;                 float* e = edge + ((size_t)u.pm * 6 + fr) * DFF + f0; *(f32x4*)e = acc[0][0][0][0] * r_ + bg0; *(f32x4*)(e + 4) = acc[0][0][0][1] * r_ + bg1;
;                 if (fr == 0) { const f32x4 bv0 = *(const f32x4*)(bpg + 128), bv1 = *(const f32x4*)(bpg + 132); float* ev = edge + ((size_t)u.pm * 6 + 4) * DFF + f0; *(f32x4*)ev = acc[0][1][0][0] * r_ + bv0; *(f32x4*)(ev + 4) = acc[0][1][0][1] * r_ + bv1; }
;             }
;             if (wr == 1 && fr >= 14) {
;                 const float r_ = GLU_RS(1, 3);
;                 float* e = edge + ((size_t)u.pm * 6 + 2 + (fr - 14)) * DFF + f0; *(f32x4*)e = acc[1][0][3][0] * r_ + bg0; *(f32x4*)(e + 4) = acc[1][0][3][1] * r_ + bg1;
;                 if (fr == 15) { const f32x4 bv0 = *(const f32x4*)(bpg + 128), bv1 = *(const f32x4*)(bpg + 132); float* ev = edge + ((size_t)u.pm * 6 + 5) * DFF + f0; *(f32x4*)ev = acc[1][1][3][0] * r_ + bv0; *(f32x4*)(ev + 4) = acc[1][1][3][1] * r_ + bv1; }
;             }
;         }
;         asm volatile("s_waitcnt lgkmcnt(0)" ::: "memory"); __builtin_amdgcn_s_barrier(); asm volatile("" ::: "memory");
; #pragma unroll
;         for (int ai = 0; ai < 2; ++ai) {
.LBB0_361:
	s_or_b64 exec, exec, s[0:1]
	s_waitcnt vmcnt(1)
	v_fmamk_f32 v120, v154, 0x3a800000, v218
	v_cmp_gt_f32_e32 vcc, s9, v120
	v_mul_f32_e32 v121, 0x4b800000, v120
	v_readlane_b32 s0, v254, 60
	v_cndmask_b32_e32 v120, v120, v121, vcc
	v_rsq_f32_e32 v120, v120
	s_waitcnt lgkmcnt(0)
	s_barrier
	v_mul_f32_e32 v121, 0x45800000, v120
	v_cndmask_b32_e32 v190, v120, v121, vcc
	v_fmamk_f32 v120, v153, 0x3a800000, v218
	v_cmp_gt_f32_e32 vcc, s9, v120
	v_mul_f32_e32 v121, 0x4b800000, v120
	v_readlane_b32 s1, v254, 61
	v_cndmask_b32_e32 v120, v120, v121, vcc
	v_rsq_f32_e32 v120, v120
	v_mov_b32_e32 v224, v2
	v_mov_b32_e32 v236, v2
	v_mov_b32_e32 v239, v2
	v_mul_f32_e32 v121, 0x45800000, v120
	v_cndmask_b32_e32 v194, v120, v121, vcc
	v_fmamk_f32 v120, v152, 0x3a800000, v218
	v_cmp_gt_f32_e32 vcc, s9, v120
	v_mul_f32_e32 v121, 0x4b800000, v120
	global_load_dwordx4 v[156:159], v[192:193], off
	global_load_dwordx4 v[152:155], v[192:193], off offset:512
	v_cndmask_b32_e32 v120, v120, v121, vcc
	v_rsq_f32_e32 v120, v120
	v_mov_b32_e32 v231, v2
	v_mov_b32_e32 v237, v2
	v_mov_b32_e32 v238, v2
	v_mul_f32_e32 v121, 0x45800000, v120
	v_cndmask_b32_e32 v208, v120, v121, vcc
	v_fmamk_f32 v120, v151, 0x3a800000, v218
	v_cmp_gt_f32_e32 vcc, s9, v120
	v_mul_f32_e32 v121, 0x4b800000, v120
	v_mov_b32_e32 v240, v2
	v_cndmask_b32_e32 v120, v120, v121, vcc
	v_rsq_f32_e32 v120, v120
	v_add_u32_e32 v187, s60, v3
	v_mov_b32_e32 v228, v2
	v_mov_b32_e32 v229, v2
	v_mul_f32_e32 v121, 0x45800000, v120
	v_cndmask_b32_e32 v210, v120, v121, vcc
	v_lshlrev_b64 v[120:121], 2, v[212:213]
	v_lshl_add_u64 v[196:197], s[0:1], 0, v[120:121]
	v_readlane_b32 s0, v254, 58
	v_readlane_b32 s1, v254, 59
	global_load_dwordx4 v[144:147], v[196:197], off
	v_lshl_add_u64 v[202:203], s[0:1], 0, v[120:121]
	global_load_dwordx4 v[148:151], v[202:203], off
	v_readlane_b32 s0, v254, 62
	v_readlane_b32 s1, v254, 63
	s_waitcnt vmcnt(3)
	v_pk_fma_f32 v[132:133], v[132:133], v[206:207], v[156:157] op_sel_hi:[1,0,1]
	v_lshl_add_u64 v[204:205], s[0:1], 0, v[120:121]
	v_readlane_b32 s0, v254, 56
	v_readlane_b32 s1, v254, 57
	global_load_dwordx4 v[136:139], v[204:205], off
	v_mov_b32_dpp v224, v132 row_ror:1 row_mask:0xf bank_mask:0xf
	v_lshl_add_u64 v[198:199], s[0:1], 0, v[120:121]
	global_load_dwordx4 v[140:143], v[198:199], off
	ds_read_b128 v[214:217], v189
	ds_read_b128 v[160:163], v191 offset:1024
	ds_read_b128 v[120:123], v191 offset:1040
	v_mov_b32_dpp v236, v133 row_ror:1 row_mask:0xf bank_mask:0xf
	s_waitcnt vmcnt(4)
	v_pk_fma_f32 v[234:235], v[128:129], v[206:207], v[152:153] op_sel_hi:[1,0,1]
	s_waitcnt lgkmcnt(2)
	v_cndmask_b32_e64 v215, v236, v215, s[38:39]
	v_cndmask_b32_e64 v214, v224, v214, s[38:39]
	v_pk_fma_f32 v[128:129], v[134:135], v[206:207], v[158:159] op_sel_hi:[1,0,1]
	v_mov_b32_dpp v231, v132 row_ror:15 row_mask:0xf bank_mask:0xf
	v_mov_b32_dpp v237, v133 row_ror:15 row_mask:0xf bank_mask:0xf
	v_mov_b32_dpp v239, v129 row_ror:1 row_mask:0xf bank_mask:0xf
	v_mov_b32_dpp v238, v128 row_ror:15 row_mask:0xf bank_mask:0xf
	v_mov_b32_dpp v240, v129 row_ror:15 row_mask:0xf bank_mask:0xf
	v_pk_fma_f32 v[124:125], v[124:125], v[210:211], v[156:157] op_sel_hi:[1,0,1]
	v_pk_fma_f32 v[126:127], v[126:127], v[210:211], v[158:159] op_sel_hi:[1,0,1]
	v_pk_fma_f32 v[116:117], v[116:117], v[210:211], v[152:153] op_sel_hi:[1,0,1]
	v_mov_b32_dpp v228, v125 row_ror:15 row_mask:0xf bank_mask:0xf
	v_mov_b32_dpp v229, v124 row_ror:1 row_mask:0xf bank_mask:0xf
	s_waitcnt vmcnt(3)
	v_pk_mul_f32 v[214:215], v[144:145], v[214:215]
	v_mov_b32_dpp v230, v125 row_ror:1 row_mask:0xf bank_mask:0xf
	v_pk_fma_f32 v[114:115], v[114:115], v[208:209], v[158:159] op_sel_hi:[1,0,1]
	s_waitcnt vmcnt(2)
	v_pk_fma_f32 v[232:233], v[132:133], v[148:149], v[214:215]
	v_cndmask_b32_e64 v133, v239, v217, s[38:39]
	v_pk_fma_f32 v[118:119], v[118:119], v[210:211], v[154:155] op_sel_hi:[1,0,1]
	v_mov_b32_dpp v215, v128 row_ror:1 row_mask:0xf bank_mask:0xf
	v_cndmask_b32_e64 v132, v215, v216, s[38:39]
	v_pk_mul_f32 v[132:133], v[146:147], v[132:133]
	v_pk_fma_f32 v[104:105], v[104:105], v[200:201], v[156:157] op_sel_hi:[1,0,1]
	v_pk_fma_f32 v[134:135], v[128:129], v[150:151], v[132:133]
	v_pk_fma_f32 v[132:133], v[130:131], v[206:207], v[154:155] op_sel_hi:[1,0,1]
	v_mov_b64_e32 v[128:129], s[82:83]
	v_mad_i64_i32 v[216:217], s[0:1], v187, s8, v[128:129]
	v_lshlrev_b64 v[130:131], 1, v[212:213]
	v_mov_b32_dpp v207, v124 row_ror:15 row_mask:0xf bank_mask:0xf
	v_lshl_add_u64 v[212:213], v[216:217], 0, v[130:131]
	v_cndmask_b32_e64 v217, v237, v228, s[40:41]
	v_cndmask_b32_e64 v216, v231, v207, s[40:41]
	v_cndmask_b32_e64 v237, v230, v236, s[38:39]
	v_cndmask_b32_e64 v236, v229, v224, s[38:39]
	v_mov_b32_dpp v231, v126 row_ror:15 row_mask:0xf bank_mask:0xf
	v_pk_mul_f32 v[236:237], v[144:145], v[236:237]
	v_pk_fma_f32 v[100:101], v[100:101], v[200:201], v[152:153] op_sel_hi:[1,0,1]
	v_mov_b32_dpp v224, v126 row_ror:1 row_mask:0xf bank_mask:0xf
	v_pk_fma_f32 v[124:125], v[124:125], v[148:149], v[236:237]
	v_pk_fma_f32 v[106:107], v[106:107], v[200:201], v[158:159] op_sel_hi:[1,0,1]
	v_pk_fma_f32 v[102:103], v[102:103], v[200:201], v[154:155] op_sel_hi:[1,0,1]
	s_waitcnt vmcnt(1)
	v_pk_fma_f32 v[216:217], v[136:137], v[216:217], v[232:233]
	s_waitcnt vmcnt(0)
; #define LAS __attribute__((address_space(3)))
; __device__ __forceinline__ float silu_f(float x) { return x * fast_rcp(1.0f + __expf(-x)); }
; __device__ __forceinline__ float dpp_ror1(float v)  { return __builtin_bit_cast(float, __builtin_amdgcn_update_dpp(0, __builtin_bit_cast(int, v), 0x121, 0xf, 0xf, false)); }
; __device__ __forceinline__ float dpp_ror15(float v) { return __builtin_bit_cast(float, __builtin_amdgcn_update_dpp(0, __builtin_bit_cast(int, v), 0x12F, 0xf, 0xf, false)); }
;     __device__ __forceinline__ void operator()(const pg8::f32x4 (&acc)[2][2][4][2], const pg8::Unit& u, int wr, int wc, int fr, int fq) const {
;     ...
;                 const f32x4 w0 = *(const f32x4*)(cw + f0 + 4 * n), w1 = *(const f32x4*)(cw + DFF + f0 + 4 * n), w2 = *(const f32x4*)(cw + 2 * DFF + f0 + 4 * n), bb = *(const f32x4*)(cb + f0 + 4 * n);
;                 const f32x4 xu = *(const LAS f32x4*)(xg + (giu * 2 + 1) * 128 + lf + 4 * n), xd = *(const LAS f32x4*)(xg + (gid * 2 + 0) * 128 + lf + 4 * n);
;                 float uv[4][4];
; #pragma unroll
;                 for (int e = 0; e < 4; ++e) {
;                     float gg[4], ur[4], dr[4];
; #pragma unroll
;                     for (int m = 0; m < 4; ++m) { gg[m] = acc[ai][0][m][n][e] * rs[m] + bgn[e]; ur[m] = dpp_ror1(gg[m]); dr[m] = dpp_ror15(gg[m]); }
; #pragma unroll
;                     for (int m = 0; m < 4; ++m) {
;                         const float up = (fr == 0) ? (m > 0 ? ur[m > 0 ? m - 1 : 0] : xu[e]) : ur[m];
;                         const float dn = (fr == 15) ? (m < 3 ? dr[m < 3 ? m + 1 : 3] : xd[e]) : dr[m];
;                         const float c = w0[e] * up + w1[e] * gg[m] + w2[e] * dn + bb[e];
;                         uv[m][e] = silu_f(c) * (acc[ai][1][m][n][e] * rs[m] + bvn[e]);
;                     }
;                 }
; #pragma unroll
;                 for (int m = 0; m < 4; ++m) {
;                     u32x2 w; w.x = cvt_pk_bf16(uv[m][0], uv[m][1]); w.y = cvt_pk_bf16(uv[m][2], uv[m][3]);
;                     *(u32x2*)(U + (size_t)(u.pm * 256 + ai * 128 + wr * 64 + m * 16 + fr) * DFF + f0 + 4 * n) = w;
;                 }
;             }
	v_pk_add_f32 v[216:217], v[140:141], v[216:217]
	s_nop 0
	v_mul_f32_e32 v214, 0xbfb8aa3b, v216
	v_exp_f32_e32 v214, v214
	s_nop 0
	v_add_f32_e32 v214, 1.0, v214
	v_rcp_f32_e32 v232, v214
	v_mul_f32_e32 v214, 0xbfb8aa3b, v217
	v_exp_f32_e32 v214, v214
	s_nop 0
	v_add_f32_e32 v214, 1.0, v214
	v_rcp_f32_e32 v233, v214
	s_nop 0
	v_pk_mul_f32 v[216:217], v[216:217], v[232:233]
	s_nop 0
	v_pk_mul_f32 v[216:217], v[234:235], v[216:217]
	v_cvt_pk_bf16_f32 v214, v216, v217
	v_cndmask_b32_e64 v216, v238, v231, s[40:41]
	v_mov_b32_dpp v235, v127 row_ror:15 row_mask:0xf bank_mask:0xf
	v_cndmask_b32_e64 v217, v240, v235, s[40:41]
	v_pk_fma_f32 v[134:135], v[138:139], v[216:217], v[134:135]
	v_cndmask_b32_e64 v232, v224, v215, s[38:39]
	v_pk_add_f32 v[134:135], v[142:143], v[134:135]
	v_mul_f32_e32 v216, 0xbfb8aa3b, v134
	v_mul_f32_e32 v215, 0xbfb8aa3b, v135
	v_exp_f32_e32 v216, v216
	v_exp_f32_e32 v215, v215
	v_mov_b32_dpp v234, v127 row_ror:1 row_mask:0xf bank_mask:0xf
	v_cndmask_b32_e64 v233, v234, v239, s[38:39]
	v_add_f32_e32 v216, 1.0, v216
	v_add_f32_e32 v215, 1.0, v215
	v_rcp_f32_e32 v216, v216
	v_rcp_f32_e32 v217, v215
	v_pk_mul_f32 v[232:233], v[146:147], v[232:233]
	v_pk_mul_f32 v[134:135], v[134:135], v[216:217]
	s_nop 0
	v_pk_mul_f32 v[132:133], v[132:133], v[134:135]
	v_pk_fma_f32 v[126:127], v[126:127], v[150:151], v[232:233]
	v_cvt_pk_bf16_f32 v215, v132, v133
	v_or_b32_e32 v132, 16, v187
	v_mad_i64_i32 v[132:133], s[0:1], v132, s8, v[128:129]
	v_lshl_add_u64 v[216:217], v[132:133], 0, v[130:131]
	v_pk_fma_f32 v[132:133], v[112:113], v[208:209], v[156:157] op_sel_hi:[1,0,1]
	s_nop 1
	v_mov_b32_dpp v134, v132 row_ror:1 row_mask:0xf bank_mask:0xf
	v_mov_b32_dpp v232, v133 row_ror:1 row_mask:0xf bank_mask:0xf
	v_pk_fma_f32 v[112:113], v[108:109], v[208:209], v[152:153] op_sel_hi:[1,0,1]
	v_cndmask_b32_e64 v109, v232, v230, s[38:39]
	v_cndmask_b32_e64 v108, v134, v229, s[38:39]
	v_mov_b32_dpp v135, v132 row_ror:15 row_mask:0xf bank_mask:0xf
	v_mov_b32_dpp v233, v133 row_ror:15 row_mask:0xf bank_mask:0xf
	v_pk_mul_f32 v[108:109], v[144:145], v[108:109]
	v_pk_fma_f32 v[132:133], v[132:133], v[148:149], v[108:109]
	v_cndmask_b32_e64 v109, v228, v233, s[40:41]
	v_cndmask_b32_e64 v108, v207, v135, s[40:41]
	v_pk_fma_f32 v[108:109], v[136:137], v[108:109], v[124:125]
	v_pk_add_f32 v[108:109], v[140:141], v[108:109]
	v_mov_b32_dpp v229, v115 row_ror:1 row_mask:0xf bank_mask:0xf
	v_mul_f32_e32 v124, 0xbfb8aa3b, v108
	v_mul_f32_e32 v125, 0xbfb8aa3b, v109
	v_exp_f32_e32 v124, v124
	v_exp_f32_e32 v125, v125
	v_mov_b32_dpp v207, v114 row_ror:1 row_mask:0xf bank_mask:0xf
	v_add_f32_e32 v124, 1.0, v124
	v_add_f32_e32 v125, 1.0, v125
	v_rcp_f32_e32 v124, v124
	v_rcp_f32_e32 v125, v125
	v_mov_b32_dpp v228, v114 row_ror:15 row_mask:0xf bank_mask:0xf
	global_store_dwordx2 v[212:213], v[214:215], off
	v_pk_mul_f32 v[108:109], v[108:109], v[124:125]
	v_mov_b32_dpp v230, v115 row_ror:15 row_mask:0xf bank_mask:0xf
	v_pk_mul_f32 v[108:109], v[116:117], v[108:109]
	v_mov_b32_e32 v153, v2
	v_cvt_pk_bf16_f32 v116, v108, v109
	v_pk_fma_f32 v[108:109], v[110:111], v[208:209], v[154:155] op_sel_hi:[1,0,1]
	v_cndmask_b32_e64 v111, v229, v234, s[38:39]
	v_cndmask_b32_e64 v110, v207, v224, s[38:39]
	v_pk_mul_f32 v[110:111], v[146:147], v[110:111]
	v_mov_b32_e32 v152, v2
	v_pk_fma_f32 v[110:111], v[114:115], v[150:151], v[110:111]
	v_cndmask_b32_e64 v115, v235, v230, s[40:41]
	v_cndmask_b32_e64 v114, v231, v228, s[40:41]
	v_pk_fma_f32 v[114:115], v[138:139], v[114:115], v[126:127]
	s_nop 0
	v_pk_add_f32 v[114:115], v[142:143], v[114:115]
	s_nop 0
	v_mul_f32_e32 v117, 0xbfb8aa3b, v114
	v_exp_f32_e32 v117, v117
	s_nop 0
	v_add_f32_e32 v117, 1.0, v117
	v_rcp_f32_e32 v124, v117
	v_mul_f32_e32 v117, 0xbfb8aa3b, v115
	v_exp_f32_e32 v117, v117
	s_nop 0
	v_add_f32_e32 v117, 1.0, v117
	v_rcp_f32_e32 v125, v117
	s_nop 0
	v_pk_mul_f32 v[114:115], v[114:115], v[124:125]
	s_nop 0
	v_pk_mul_f32 v[114:115], v[118:119], v[114:115]
	v_cvt_pk_bf16_f32 v117, v114, v115
	v_or_b32_e32 v114, 32, v187
	v_mad_i64_i32 v[114:115], s[0:1], v114, s8, v[128:129]
	v_lshl_add_u64 v[214:215], v[114:115], 0, v[130:131]
	v_mov_b32_dpp v114, v104 row_ror:1 row_mask:0xf bank_mask:0xf
	v_mov_b32_dpp v115, v105 row_ror:1 row_mask:0xf bank_mask:0xf
	v_cndmask_b32_e64 v115, v115, v232, s[38:39]
	v_cndmask_b32_e64 v114, v114, v134, s[38:39]
	v_mov_b32_dpp v118, v104 row_ror:15 row_mask:0xf bank_mask:0xf
	v_mov_b32_dpp v119, v105 row_ror:15 row_mask:0xf bank_mask:0xf
	v_pk_mul_f32 v[114:115], v[144:145], v[114:115]
	global_store_dwordx2 v[216:217], v[116:117], off
	s_waitcnt lgkmcnt(1)
; #define LAS __attribute__((address_space(3)))
; __device__ __forceinline__ float silu_f(float x) { return x * fast_rcp(1.0f + __expf(-x)); }
; __device__ __forceinline__ float dpp_ror1(float v)  { return __builtin_bit_cast(float, __builtin_amdgcn_update_dpp(0, __builtin_bit_cast(int, v), 0x121, 0xf, 0xf, false)); }
; __device__ __forceinline__ float dpp_ror15(float v) { return __builtin_bit_cast(float, __builtin_amdgcn_update_dpp(0, __builtin_bit_cast(int, v), 0x12F, 0xf, 0xf, false)); }
;     __device__ __forceinline__ void operator()(const pg8::f32x4 (&acc)[2][2][4][2], const pg8::Unit& u, int wr, int wc, int fr, int fq) const {
;     ...
;                 const f32x4 w0 = *(const f32x4*)(cw + f0 + 4 * n), w1 = *(const f32x4*)(cw + DFF + f0 + 4 * n), w2 = *(const f32x4*)(cw + 2 * DFF + f0 + 4 * n), bb = *(const f32x4*)(cb + f0 + 4 * n);
;                 const f32x4 xu = *(const LAS f32x4*)(xg + (giu * 2 + 1) * 128 + lf + 4 * n), xd = *(const LAS f32x4*)(xg + (gid * 2 + 0) * 128 + lf + 4 * n);
;                 float uv[4][4];
; #pragma unroll
;                 for (int e = 0; e < 4; ++e) {
;                     float gg[4], ur[4], dr[4];
; #pragma unroll
;                     for (int m = 0; m < 4; ++m) { gg[m] = acc[ai][0][m][n][e] * rs[m] + bgn[e]; ur[m] = dpp_ror1(gg[m]); dr[m] = dpp_ror15(gg[m]); }
; #pragma unroll
;                     for (int m = 0; m < 4; ++m) {
;                         const float up = (fr == 0) ? (m > 0 ? ur[m > 0 ? m - 1 : 0] : xu[e]) : ur[m];
;                         const float dn = (fr == 15) ? (m < 3 ? dr[m < 3 ? m + 1 : 3] : xd[e]) : dr[m];
;                         const float c = w0[e] * up + w1[e] * gg[m] + w2[e] * dn + bb[e];
;                         uv[m][e] = silu_f(c) * (acc[ai][1][m][n][e] * rs[m] + bvn[e]);
;                     }
;                 }
; #pragma unroll
;                 for (int m = 0; m < 4; ++m) {
;                     u32x2 w; w.x = cvt_pk_bf16(uv[m][0], uv[m][1]); w.y = cvt_pk_bf16(uv[m][2], uv[m][3]);
;                     *(u32x2*)(U + (size_t)(u.pm * 256 + ai * 128 + wr * 64 + m * 16 + fr) * DFF + f0 + 4 * n) = w;
;                 }
;             }
	v_cndmask_b32_e64 v117, v119, v161, s[40:41]
	v_cndmask_b32_e64 v116, v118, v160, s[40:41]
	v_pk_fma_f32 v[104:105], v[104:105], v[148:149], v[114:115]
	v_mov_b32_e32 v144, v2
	v_pk_fma_f32 v[104:105], v[136:137], v[116:117], v[104:105]
	v_pk_add_f32 v[104:105], v[140:141], v[104:105]
	v_mov_b32_e32 v148, v2
	v_mul_f32_e32 v114, 0xbfb8aa3b, v104
	v_mul_f32_e32 v115, 0xbfb8aa3b, v105
	v_exp_f32_e32 v114, v114
	v_exp_f32_e32 v115, v115
	v_mov_b32_dpp v116, v107 row_ror:15 row_mask:0xf bank_mask:0xf
	v_mov_b32_e32 v145, v2
	v_add_f32_e32 v114, 1.0, v114
	v_add_f32_e32 v115, 1.0, v115
	v_rcp_f32_e32 v114, v114
	v_rcp_f32_e32 v115, v115
	v_mov_b32_e32 v149, v2
	v_pk_mul_f32 v[104:105], v[104:105], v[114:115]
	s_nop 0
	v_pk_mul_f32 v[100:101], v[100:101], v[104:105]
	v_cndmask_b32_e64 v105, v233, v119, s[40:41]
	v_cndmask_b32_e64 v104, v135, v118, s[40:41]
	v_pk_fma_f32 v[104:105], v[136:137], v[104:105], v[132:133]
	v_cvt_pk_bf16_f32 v100, v100, v101
	v_pk_add_f32 v[104:105], v[140:141], v[104:105]
	v_mul_f32_e32 v114, 0xbfb8aa3b, v104
	v_mul_f32_e32 v115, 0xbfb8aa3b, v105
	v_exp_f32_e32 v114, v114
	v_exp_f32_e32 v115, v115
	v_mov_b32_dpp v101, v106 row_ror:1 row_mask:0xf bank_mask:0xf
	v_add_f32_e32 v114, 1.0, v114
	v_add_f32_e32 v115, 1.0, v115
	v_rcp_f32_e32 v114, v114
	v_rcp_f32_e32 v115, v115
	s_nop 0
	v_pk_mul_f32 v[104:105], v[104:105], v[114:115]
	s_nop 0
	v_pk_mul_f32 v[104:105], v[112:113], v[104:105]
	v_cvt_pk_bf16_f32 v104, v104, v105
	v_mov_b32_dpp v112, v107 row_ror:1 row_mask:0xf bank_mask:0xf
	v_cndmask_b32_e64 v113, v112, v229, s[38:39]
	v_cndmask_b32_e64 v112, v101, v207, s[38:39]
	v_mov_b32_dpp v105, v106 row_ror:15 row_mask:0xf bank_mask:0xf
	v_pk_mul_f32 v[112:113], v[146:147], v[112:113]
	v_cndmask_b32_e64 v115, v116, v163, s[40:41]
	v_cndmask_b32_e64 v114, v105, v162, s[40:41]
	v_pk_fma_f32 v[106:107], v[106:107], v[150:151], v[112:113]
	v_mov_b32_e32 v146, v2
	v_pk_fma_f32 v[106:107], v[138:139], v[114:115], v[106:107]
	v_mov_b32_e32 v151, v2
	v_pk_add_f32 v[106:107], v[142:143], v[106:107]
	v_mov_b32_e32 v147, v2
	v_mul_f32_e32 v101, 0xbfb8aa3b, v106
	v_exp_f32_e32 v101, v101
	v_mov_b32_e32 v150, v2
	v_add_f32_e32 v101, 1.0, v101
	v_rcp_f32_e32 v112, v101
	v_mul_f32_e32 v101, 0xbfb8aa3b, v107
	v_exp_f32_e32 v101, v101
	s_nop 0
	v_add_f32_e32 v101, 1.0, v101
	v_rcp_f32_e32 v113, v101
	s_nop 0
	v_pk_mul_f32 v[106:107], v[106:107], v[112:113]
	s_nop 0
	v_pk_mul_f32 v[102:103], v[102:103], v[106:107]
	v_cndmask_b32_e64 v107, v230, v116, s[40:41]
	v_cndmask_b32_e64 v106, v228, v105, s[40:41]
	v_pk_fma_f32 v[106:107], v[138:139], v[106:107], v[110:111]
	s_nop 0
	v_pk_add_f32 v[106:107], v[142:143], v[106:107]
	v_mul_f32_e32 v101, 0xbfb8aa3b, v106
	v_exp_f32_e32 v101, v101
	s_nop 0
	v_add_f32_e32 v101, 1.0, v101
	v_rcp_f32_e32 v110, v101
	v_mul_f32_e32 v101, 0xbfb8aa3b, v107
	v_exp_f32_e32 v101, v101
	s_nop 0
	v_add_f32_e32 v101, 1.0, v101
	v_rcp_f32_e32 v111, v101
	v_cvt_pk_bf16_f32 v101, v102, v103
	v_or_b32_e32 v102, 48, v187
	v_mad_i64_i32 v[102:103], s[0:1], v102, s8, v[128:129]
	v_pk_mul_f32 v[106:107], v[106:107], v[110:111]
	v_lshl_add_u64 v[136:137], v[102:103], 0, v[130:131]
	v_pk_mul_f32 v[106:107], v[108:109], v[106:107]
	global_store_dwordx2 v[136:137], v[100:101], off
	v_cvt_pk_bf16_f32 v105, v106, v107
	global_store_dwordx2 v[214:215], v[104:105], off
	s_movk_i32 s0, 0x2000
	global_load_dwordx4 v[124:127], v[192:193], off offset:16
	global_load_dwordx4 v[116:119], v[192:193], off offset:528
	global_load_dwordx4 v[108:111], v[196:197], off offset:16
	v_add_co_u32_e32 v132, vcc, s0, v196
	s_movk_i32 s0, 0x5000
	s_nop 0
	v_addc_co_u32_e32 v133, vcc, 0, v197, vcc
	global_load_dwordx4 v[112:115], v[132:133], off offset:3088
	v_add_co_u32_e32 v134, vcc, s0, v196
	s_waitcnt vmcnt(3)
	v_pk_fma_f32 v[92:93], v[92:93], v[206:207], v[124:125] op_sel_hi:[1,0,1]
	v_addc_co_u32_e32 v135, vcc, 0, v197, vcc
	global_load_dwordx4 v[100:103], v[134:135], off offset:2064
	global_load_dwordx4 v[104:107], v[198:199], off offset:16
	ds_read_b128 v[138:141], v195
	v_mov_b32_dpp v142, v92 row_ror:1 row_mask:0xf bank_mask:0xf
	v_mov_b32_dpp v144, v93 row_ror:1 row_mask:0xf bank_mask:0xf
	v_pk_fma_f32 v[94:95], v[94:95], v[206:207], v[126:127] op_sel_hi:[1,0,1]
	v_mov_b32_dpp v143, v92 row_ror:15 row_mask:0xf bank_mask:0xf
	s_waitcnt lgkmcnt(0)
	v_cndmask_b32_e64 v139, v144, v139, s[38:39]
	v_cndmask_b32_e64 v138, v142, v138, s[38:39]
	s_waitcnt vmcnt(3)
	v_pk_mul_f32 v[138:139], v[108:109], v[138:139]
	v_mov_b32_dpp v146, v94 row_ror:1 row_mask:0xf bank_mask:0xf
	v_mov_b32_dpp v148, v95 row_ror:1 row_mask:0xf bank_mask:0xf
	v_mov_b32_dpp v145, v93 row_ror:15 row_mask:0xf bank_mask:0xf
	s_waitcnt vmcnt(2)
; #define LAS __attribute__((address_space(3)))
; __device__ __forceinline__ float silu_f(float x) { return x * fast_rcp(1.0f + __expf(-x)); }
; __device__ __forceinline__ float dpp_ror1(float v)  { return __builtin_bit_cast(float, __builtin_amdgcn_update_dpp(0, __builtin_bit_cast(int, v), 0x121, 0xf, 0xf, false)); }
; __device__ __forceinline__ float dpp_ror15(float v) { return __builtin_bit_cast(float, __builtin_amdgcn_update_dpp(0, __builtin_bit_cast(int, v), 0x12F, 0xf, 0xf, false)); }
;     __device__ __forceinline__ void operator()(const pg8::f32x4 (&acc)[2][2][4][2], const pg8::Unit& u, int wr, int wc, int fr, int fq) const {
;     ...
;                 const f32x4 w0 = *(const f32x4*)(cw + f0 + 4 * n), w1 = *(const f32x4*)(cw + DFF + f0 + 4 * n), w2 = *(const f32x4*)(cw + 2 * DFF + f0 + 4 * n), bb = *(const f32x4*)(cb + f0 + 4 * n);
;                 const f32x4 xu = *(const LAS f32x4*)(xg + (giu * 2 + 1) * 128 + lf + 4 * n), xd = *(const LAS f32x4*)(xg + (gid * 2 + 0) * 128 + lf + 4 * n);
;                 float uv[4][4];
; #pragma unroll
;                 for (int e = 0; e < 4; ++e) {
;                     float gg[4], ur[4], dr[4];
; #pragma unroll
;                     for (int m = 0; m < 4; ++m) { gg[m] = acc[ai][0][m][n][e] * rs[m] + bgn[e]; ur[m] = dpp_ror1(gg[m]); dr[m] = dpp_ror15(gg[m]); }
; #pragma unroll
;                     for (int m = 0; m < 4; ++m) {
;                         const float up = (fr == 0) ? (m > 0 ? ur[m > 0 ? m - 1 : 0] : xu[e]) : ur[m];
;                         const float dn = (fr == 15) ? (m < 3 ? dr[m < 3 ? m + 1 : 3] : xd[e]) : dr[m];
;                         const float c = w0[e] * up + w1[e] * gg[m] + w2[e] * dn + bb[e];
;                         uv[m][e] = silu_f(c) * (acc[ai][1][m][n][e] * rs[m] + bvn[e]);
;                     }
;                 }
; #pragma unroll
;                 for (int m = 0; m < 4; ++m) {
;                     u32x2 w; w.x = cvt_pk_bf16(uv[m][0], uv[m][1]); w.y = cvt_pk_bf16(uv[m][2], uv[m][3]);
;                     *(u32x2*)(U + (size_t)(u.pm * 256 + ai * 128 + wr * 64 + m * 16 + fr) * DFF + f0 + 4 * n) = w;
;                 }
;             }
	v_pk_fma_f32 v[92:93], v[92:93], v[112:113], v[138:139]
	v_cndmask_b32_e64 v139, v148, v141, s[38:39]
	v_cndmask_b32_e64 v138, v146, v140, s[38:39]
	v_pk_fma_f32 v[88:89], v[88:89], v[210:211], v[124:125] op_sel_hi:[1,0,1]
	v_pk_mul_f32 v[138:139], v[110:111], v[138:139]
	v_mov_b32_dpp v147, v94 row_ror:15 row_mask:0xf bank_mask:0xf
	v_mov_b32_dpp v151, v88 row_ror:15 row_mask:0xf bank_mask:0xf
	v_mov_b32_dpp v153, v89 row_ror:15 row_mask:0xf bank_mask:0xf
	v_mov_b32_dpp v149, v95 row_ror:15 row_mask:0xf bank_mask:0xf
	v_pk_fma_f32 v[94:95], v[94:95], v[114:115], v[138:139]
	v_cndmask_b32_e64 v139, v145, v153, s[40:41]
	v_cndmask_b32_e64 v138, v143, v151, s[40:41]
	v_mov_b32_dpp v150, v88 row_ror:1 row_mask:0xf bank_mask:0xf
	v_mov_b32_dpp v152, v89 row_ror:1 row_mask:0xf bank_mask:0xf
	v_cndmask_b32_e64 v141, v152, v144, s[38:39]
	v_cndmask_b32_e64 v140, v150, v142, s[38:39]
	v_pk_mul_f32 v[140:141], v[108:109], v[140:141]
	v_pk_fma_f32 v[90:91], v[90:91], v[210:211], v[126:127] op_sel_hi:[1,0,1]
	v_pk_fma_f32 v[88:89], v[88:89], v[112:113], v[140:141]
	v_pk_fma_f32 v[96:97], v[96:97], v[206:207], v[116:117] op_sel_hi:[1,0,1]
	v_mov_b32_dpp v141, v90 row_ror:15 row_mask:0xf bank_mask:0xf
	v_mov_b32_dpp v143, v91 row_ror:15 row_mask:0xf bank_mask:0xf
	v_pk_fma_f32 v[98:99], v[98:99], v[206:207], v[118:119] op_sel_hi:[1,0,1]
	v_pk_fma_f32 v[84:85], v[84:85], v[210:211], v[116:117] op_sel_hi:[1,0,1]
	v_mov_b32_dpp v140, v90 row_ror:1 row_mask:0xf bank_mask:0xf
	v_mov_b32_dpp v142, v91 row_ror:1 row_mask:0xf bank_mask:0xf
	v_pk_fma_f32 v[82:83], v[82:83], v[208:209], v[126:127] op_sel_hi:[1,0,1]
	v_pk_fma_f32 v[86:87], v[86:87], v[210:211], v[118:119] op_sel_hi:[1,0,1]
	v_pk_fma_f32 v[68:69], v[68:69], v[200:201], v[124:125] op_sel_hi:[1,0,1]
	v_pk_fma_f32 v[72:73], v[72:73], v[200:201], v[116:117] op_sel_hi:[1,0,1]
	v_pk_fma_f32 v[70:71], v[70:71], v[200:201], v[126:127] op_sel_hi:[1,0,1]
	v_pk_fma_f32 v[74:75], v[74:75], v[200:201], v[118:119] op_sel_hi:[1,0,1]
	s_andn2_b64 vcc, exec, s[42:43]
	s_waitcnt vmcnt(1)
	v_pk_fma_f32 v[92:93], v[100:101], v[138:139], v[92:93]
	s_waitcnt vmcnt(0)
	v_pk_add_f32 v[92:93], v[104:105], v[92:93]
	s_nop 0
	v_mul_f32_e32 v138, 0xbfb8aa3b, v92
	v_mul_f32_e32 v139, 0xbfb8aa3b, v93
	v_exp_f32_e32 v138, v138
	v_exp_f32_e32 v139, v139
	v_add_f32_e32 v138, 1.0, v138
	v_add_f32_e32 v139, 1.0, v139
	v_rcp_f32_e32 v138, v138
	v_rcp_f32_e32 v139, v139
	s_nop 0
	v_pk_mul_f32 v[92:93], v[92:93], v[138:139]
	s_nop 0
	v_pk_mul_f32 v[92:93], v[96:97], v[92:93]
	v_cndmask_b32_e64 v97, v149, v143, s[40:41]
	v_cndmask_b32_e64 v96, v147, v141, s[40:41]
	v_pk_fma_f32 v[94:95], v[102:103], v[96:97], v[94:95]
	v_cvt_pk_bf16_f32 v92, v92, v93
	v_pk_add_f32 v[94:95], v[106:107], v[94:95]
	v_cndmask_b32_e64 v139, v142, v148, s[38:39]
	v_mul_f32_e32 v93, 0xbfb8aa3b, v94
	v_exp_f32_e32 v93, v93
	v_cndmask_b32_e64 v138, v140, v146, s[38:39]
	v_pk_mul_f32 v[138:139], v[110:111], v[138:139]
	v_add_f32_e32 v93, 1.0, v93
	v_rcp_f32_e32 v96, v93
	v_mul_f32_e32 v93, 0xbfb8aa3b, v95
	v_exp_f32_e32 v93, v93
	v_pk_fma_f32 v[90:91], v[90:91], v[114:115], v[138:139]
	v_add_f32_e32 v93, 1.0, v93
	v_rcp_f32_e32 v97, v93
	v_mov_b32_dpp v138, v83 row_ror:1 row_mask:0xf bank_mask:0xf
	v_mov_b32_dpp v139, v83 row_ror:15 row_mask:0xf bank_mask:0xf
	v_pk_mul_f32 v[94:95], v[94:95], v[96:97]
	s_nop 0
	v_pk_mul_f32 v[94:95], v[98:99], v[94:95]
	v_cvt_pk_bf16_f32 v93, v94, v95
	global_store_dwordx2 v[212:213], v[92:93], off offset:8
	v_pk_fma_f32 v[92:93], v[80:81], v[208:209], v[124:125] op_sel_hi:[1,0,1]
	s_nop 1
	v_mov_b32_dpp v96, v93 row_ror:1 row_mask:0xf bank_mask:0xf
	v_mov_b32_dpp v94, v92 row_ror:1 row_mask:0xf bank_mask:0xf
	v_pk_fma_f32 v[80:81], v[76:77], v[208:209], v[116:117] op_sel_hi:[1,0,1]
	v_cndmask_b32_e64 v77, v96, v152, s[38:39]
	v_cndmask_b32_e64 v76, v94, v150, s[38:39]
	v_mov_b32_dpp v95, v92 row_ror:15 row_mask:0xf bank_mask:0xf
	v_mov_b32_dpp v97, v93 row_ror:15 row_mask:0xf bank_mask:0xf
	v_pk_mul_f32 v[76:77], v[108:109], v[76:77]
	v_pk_fma_f32 v[92:93], v[92:93], v[112:113], v[76:77]
	v_cndmask_b32_e64 v77, v153, v97, s[40:41]
	v_cndmask_b32_e64 v76, v151, v95, s[40:41]
	v_pk_fma_f32 v[76:77], v[100:101], v[76:77], v[88:89]
	v_mov_b32_dpp v98, v82 row_ror:1 row_mask:0xf bank_mask:0xf
	v_pk_add_f32 v[76:77], v[104:105], v[76:77]
	v_mul_f32_e32 v88, 0xbfb8aa3b, v76
	v_mul_f32_e32 v89, 0xbfb8aa3b, v77
	v_exp_f32_e32 v88, v88
	v_exp_f32_e32 v89, v89
	v_mov_b32_dpp v99, v82 row_ror:15 row_mask:0xf bank_mask:0xf
	v_add_f32_e32 v88, 1.0, v88
	v_add_f32_e32 v89, 1.0, v89
	v_rcp_f32_e32 v88, v88
	v_rcp_f32_e32 v89, v89
	s_nop 0
	v_pk_mul_f32 v[76:77], v[76:77], v[88:89]
	s_nop 0
	v_pk_mul_f32 v[76:77], v[84:85], v[76:77]
	s_nop 0
	v_cvt_pk_bf16_f32 v84, v76, v77
	v_pk_fma_f32 v[76:77], v[78:79], v[208:209], v[118:119] op_sel_hi:[1,0,1]
	v_cndmask_b32_e64 v79, v138, v142, s[38:39]
	v_cndmask_b32_e64 v78, v98, v140, s[38:39]
	v_pk_mul_f32 v[78:79], v[110:111], v[78:79]
	s_nop 0
	v_pk_fma_f32 v[78:79], v[82:83], v[114:115], v[78:79]
	v_cndmask_b32_e64 v83, v143, v139, s[40:41]
	v_cndmask_b32_e64 v82, v141, v99, s[40:41]
	v_pk_fma_f32 v[82:83], v[102:103], v[82:83], v[90:91]
	s_nop 0
	v_pk_add_f32 v[82:83], v[106:107], v[82:83]
	s_nop 0
	v_mul_f32_e32 v85, 0xbfb8aa3b, v82
	v_exp_f32_e32 v85, v85
	s_nop 0
	v_add_f32_e32 v85, 1.0, v85
	v_rcp_f32_e32 v88, v85
	v_mul_f32_e32 v85, 0xbfb8aa3b, v83
	v_exp_f32_e32 v85, v85
	s_nop 0
	v_add_f32_e32 v85, 1.0, v85
	v_rcp_f32_e32 v89, v85
	s_nop 0
	v_pk_mul_f32 v[82:83], v[82:83], v[88:89]
	s_nop 0
	v_pk_mul_f32 v[82:83], v[86:87], v[82:83]
	v_cvt_pk_bf16_f32 v85, v82, v83
; #define LAS __attribute__((address_space(3)))
; __device__ __forceinline__ float silu_f(float x) { return x * fast_rcp(1.0f + __expf(-x)); }
; __device__ __forceinline__ float dpp_ror1(float v)  { return __builtin_bit_cast(float, __builtin_amdgcn_update_dpp(0, __builtin_bit_cast(int, v), 0x121, 0xf, 0xf, false)); }
;     __device__ __forceinline__ void operator()(const pg8::f32x4 (&acc)[2][2][4][2], const pg8::Unit& u, int wr, int wc, int fr, int fq) const {
;     ...
;         for (int ai = 0; ai < 2; ++ai) {
;             const int gi = 2 * ai + wr, giu = gi > 0 ? gi - 1 : 0, gid = gi < 3 ? gi + 1 : 3;
;             float rs[4];
; #pragma unroll
;             for (int m = 0; m < 4; ++m) rs[m] = GLU_RS(ai, m);
; #pragma unroll
;             for (int n = 0; n < 2; ++n) {
;                 const f32x4 bgn = *(const f32x4*)(bpg + 4 * n), bvn = *(const f32x4*)(bpg + 128 + 4 * n);
;                 const f32x4 w0 = *(const f32x4*)(cw + f0 + 4 * n), w1 = *(const f32x4*)(cw + DFF + f0 + 4 * n), w2 = *(const f32x4*)(cw + 2 * DFF + f0 + 4 * n), bb = *(const f32x4*)(cb + f0 + 4 * n);
;                 const f32x4 xu = *(const LAS f32x4*)(xg + (giu * 2 + 1) * 128 + lf + 4 * n), xd = *(const LAS f32x4*)(xg + (gid * 2 + 0) * 128 + lf + 4 * n);
;                 float uv[4][4];
; #pragma unroll
;                 for (int e = 0; e < 4; ++e) {
;                     float gg[4], ur[4], dr[4];
; #pragma unroll
;                     for (int m = 0; m < 4; ++m) { gg[m] = acc[ai][0][m][n][e] * rs[m] + bgn[e]; ur[m] = dpp_ror1(gg[m]); dr[m] = dpp_ror15(gg[m]); }
; #pragma unroll
;                     for (int m = 0; m < 4; ++m) {
;                         const float up = (fr == 0) ? (m > 0 ? ur[m > 0 ? m - 1 : 0] : xu[e]) : ur[m];
;                         const float dn = (fr == 15) ? (m < 3 ? dr[m < 3 ? m + 1 : 3] : xd[e]) : dr[m];
;                         const float c = w0[e] * up + w1[e] * gg[m] + w2[e] * dn + bb[e];
;                         uv[m][e] = silu_f(c) * (acc[ai][1][m][n][e] * rs[m] + bvn[e]);
;                     }
;                 }
; #pragma unroll
;                 for (int m = 0; m < 4; ++m) {
;                     u32x2 w; w.x = cvt_pk_bf16(uv[m][0], uv[m][1]); w.y = cvt_pk_bf16(uv[m][2], uv[m][3]);
;                     *(u32x2*)(U + (size_t)(u.pm * 256 + ai * 128 + wr * 64 + m * 16 + fr) * DFF + f0 + 4 * n) = w;
;                 }
;             }
	v_mov_b32_dpp v82, v68 row_ror:1 row_mask:0xf bank_mask:0xf
	v_mov_b32_dpp v83, v69 row_ror:1 row_mask:0xf bank_mask:0xf
	v_cndmask_b32_e64 v83, v83, v96, s[38:39]
	v_cndmask_b32_e64 v82, v82, v94, s[38:39]
	v_mov_b32_dpp v86, v68 row_ror:15 row_mask:0xf bank_mask:0xf
	v_mov_b32_dpp v87, v69 row_ror:15 row_mask:0xf bank_mask:0xf
	v_pk_mul_f32 v[82:83], v[108:109], v[82:83]
	global_store_dwordx2 v[216:217], v[84:85], off offset:8
	v_cndmask_b32_e64 v85, v87, v121, s[40:41]
	v_cndmask_b32_e64 v84, v86, v120, s[40:41]
	v_pk_fma_f32 v[68:69], v[68:69], v[112:113], v[82:83]
	v_mov_b32_e32 v112, v2
	v_pk_fma_f32 v[68:69], v[100:101], v[84:85], v[68:69]
	v_pk_add_f32 v[68:69], v[104:105], v[68:69]
	v_mov_b32_e32 v109, v2
	v_mul_f32_e32 v82, 0xbfb8aa3b, v68
	v_mul_f32_e32 v83, 0xbfb8aa3b, v69
	v_exp_f32_e32 v82, v82
	v_exp_f32_e32 v83, v83
	v_mov_b32_dpp v84, v71 row_ror:15 row_mask:0xf bank_mask:0xf
	v_mov_b32_e32 v108, v2
	v_add_f32_e32 v82, 1.0, v82
	v_add_f32_e32 v83, 1.0, v83
	v_rcp_f32_e32 v82, v82
	v_rcp_f32_e32 v83, v83
	s_nop 0
	v_pk_mul_f32 v[68:69], v[68:69], v[82:83]
	s_nop 0
	v_pk_mul_f32 v[68:69], v[72:73], v[68:69]
	v_cndmask_b32_e64 v73, v97, v87, s[40:41]
	v_cndmask_b32_e64 v72, v95, v86, s[40:41]
	v_pk_fma_f32 v[72:73], v[100:101], v[72:73], v[92:93]
	v_cvt_pk_bf16_f32 v68, v68, v69
	v_pk_add_f32 v[72:73], v[104:105], v[72:73]
	v_mul_f32_e32 v82, 0xbfb8aa3b, v72
	v_mul_f32_e32 v83, 0xbfb8aa3b, v73
	v_exp_f32_e32 v82, v82
	v_exp_f32_e32 v83, v83
	v_mov_b32_dpp v69, v70 row_ror:1 row_mask:0xf bank_mask:0xf
	v_mov_b32_e32 v101, v2
	v_add_f32_e32 v82, 1.0, v82
	v_add_f32_e32 v83, 1.0, v83
	v_rcp_f32_e32 v82, v82
	v_rcp_f32_e32 v83, v83
	v_mov_b32_e32 v104, v2
	v_mov_b32_e32 v105, v2
	v_add_u32_e32 v100, 0x80, v187
	v_pk_mul_f32 v[72:73], v[72:73], v[82:83]
	v_cndmask_b32_e64 v83, v84, v123, s[40:41]
	v_pk_mul_f32 v[72:73], v[80:81], v[72:73]
	v_cvt_pk_bf16_f32 v72, v72, v73
	v_mov_b32_dpp v80, v71 row_ror:1 row_mask:0xf bank_mask:0xf
	v_cndmask_b32_e64 v81, v80, v138, s[38:39]
	v_cndmask_b32_e64 v80, v69, v98, s[38:39]
	v_mov_b32_dpp v73, v70 row_ror:15 row_mask:0xf bank_mask:0xf
	v_pk_mul_f32 v[80:81], v[110:111], v[80:81]
	v_cndmask_b32_e64 v82, v73, v122, s[40:41]
	v_pk_fma_f32 v[70:71], v[70:71], v[114:115], v[80:81]
	v_mov_b32_e32 v110, v2
	v_pk_fma_f32 v[70:71], v[102:103], v[82:83], v[70:71]
	v_mov_b32_e32 v111, v2
	v_pk_add_f32 v[70:71], v[106:107], v[70:71]
	s_nop 0
	v_mul_f32_e32 v69, 0xbfb8aa3b, v70
	v_exp_f32_e32 v69, v69
	s_nop 0
	v_add_f32_e32 v69, 1.0, v69
	v_rcp_f32_e32 v80, v69
	v_mul_f32_e32 v69, 0xbfb8aa3b, v71
	v_exp_f32_e32 v69, v69
	s_nop 0
	v_add_f32_e32 v69, 1.0, v69
	v_rcp_f32_e32 v81, v69
	s_nop 0
	v_pk_mul_f32 v[70:71], v[70:71], v[80:81]
	s_nop 0
	v_pk_mul_f32 v[70:71], v[74:75], v[70:71]
	v_cndmask_b32_e64 v75, v139, v84, s[40:41]
	v_cndmask_b32_e64 v74, v99, v73, s[40:41]
	v_pk_fma_f32 v[74:75], v[102:103], v[74:75], v[78:79]
	v_pk_add_f32 v[74:75], v[106:107], v[74:75]
	v_mul_f32_e32 v69, 0xbfb8aa3b, v74
	v_exp_f32_e32 v69, v69
	v_mov_b32_e32 v107, v2
	v_mov_b32_e32 v106, v2
	v_add_f32_e32 v69, 1.0, v69
	v_rcp_f32_e32 v78, v69
	v_mul_f32_e32 v69, 0xbfb8aa3b, v75
	v_exp_f32_e32 v69, v69
	s_nop 0
	v_add_f32_e32 v69, 1.0, v69
	v_rcp_f32_e32 v79, v69
	v_cvt_pk_bf16_f32 v69, v70, v71
	global_store_dwordx2 v[136:137], v[68:69], off offset:8
	v_pk_mul_f32 v[74:75], v[74:75], v[78:79]
	s_nop 0
	v_pk_mul_f32 v[74:75], v[76:77], v[74:75]
	s_nop 0
	v_cvt_pk_bf16_f32 v73, v74, v75
	global_store_dwordx2 v[214:215], v[72:73], off offset:8
	global_load_dwordx4 v[88:91], v[192:193], off
	global_load_dwordx4 v[84:87], v[192:193], off offset:512
	global_load_dwordx4 v[76:79], v[196:197], off
	global_load_dwordx4 v[80:83], v[202:203], off
	global_load_dwordx4 v[68:71], v[204:205], off
	global_load_dwordx4 v[72:75], v[198:199], off
	ds_read_b128 v[96:99], v201
	ds_read_b128 v[92:95], v225 offset:1024
	s_waitcnt vmcnt(5)
	v_pk_fma_f32 v[64:65], v[64:65], v[188:189], v[88:89] op_sel_hi:[1,0,1]
	s_nop 1
	v_mov_b32_dpp v102, v64 row_ror:1 row_mask:0xf bank_mask:0xf
	v_mov_b32_dpp v103, v65 row_ror:1 row_mask:0xf bank_mask:0xf
	s_waitcnt lgkmcnt(1)
	v_cndmask_b32_e64 v97, v103, v97, s[38:39]
	v_cndmask_b32_e64 v96, v102, v96, s[38:39]
	v_pk_fma_f32 v[66:67], v[66:67], v[188:189], v[90:91] op_sel_hi:[1,0,1]
	v_pk_fma_f32 v[56:57], v[56:57], v[194:195], v[88:89] op_sel_hi:[1,0,1]
	v_mov_b32_dpp v101, v64 row_ror:15 row_mask:0xf bank_mask:0xf
	v_mov_b32_dpp v104, v65 row_ror:15 row_mask:0xf bank_mask:0xf
	s_waitcnt vmcnt(3)
	v_pk_mul_f32 v[96:97], v[76:77], v[96:97]
	v_mov_b32_dpp v105, v66 row_ror:1 row_mask:0xf bank_mask:0xf
	v_mov_b32_dpp v107, v67 row_ror:1 row_mask:0xf bank_mask:0xf
	v_mov_b32_dpp v110, v56 row_ror:15 row_mask:0xf bank_mask:0xf
	v_mov_b32_dpp v112, v57 row_ror:15 row_mask:0xf bank_mask:0xf
	s_waitcnt vmcnt(2)
	v_pk_fma_f32 v[64:65], v[64:65], v[80:81], v[96:97]
	v_cndmask_b32_e64 v97, v107, v99, s[38:39]
	v_cndmask_b32_e64 v96, v105, v98, s[38:39]
	v_cndmask_b32_e64 v99, v104, v112, s[40:41]
	v_cndmask_b32_e64 v98, v101, v110, s[40:41]
	s_waitcnt vmcnt(1)
	v_pk_fma_f32 v[64:65], v[68:69], v[98:99], v[64:65]
	v_pk_mul_f32 v[96:97], v[78:79], v[96:97]
	s_waitcnt vmcnt(0)
; #define LAS __attribute__((address_space(3)))
; __device__ __forceinline__ float silu_f(float x) { return x * fast_rcp(1.0f + __expf(-x)); }
; __device__ __forceinline__ float dpp_ror1(float v)  { return __builtin_bit_cast(float, __builtin_amdgcn_update_dpp(0, __builtin_bit_cast(int, v), 0x121, 0xf, 0xf, false)); }
; __device__ __forceinline__ float dpp_ror15(float v) { return __builtin_bit_cast(float, __builtin_amdgcn_update_dpp(0, __builtin_bit_cast(int, v), 0x12F, 0xf, 0xf, false)); }
;     __device__ __forceinline__ void operator()(const pg8::f32x4 (&acc)[2][2][4][2], const pg8::Unit& u, int wr, int wc, int fr, int fq) const {
;     ...
;                 const f32x4 w0 = *(const f32x4*)(cw + f0 + 4 * n), w1 = *(const f32x4*)(cw + DFF + f0 + 4 * n), w2 = *(const f32x4*)(cw + 2 * DFF + f0 + 4 * n), bb = *(const f32x4*)(cb + f0 + 4 * n);
;                 const f32x4 xu = *(const LAS f32x4*)(xg + (giu * 2 + 1) * 128 + lf + 4 * n), xd = *(const LAS f32x4*)(xg + (gid * 2 + 0) * 128 + lf + 4 * n);
;                 float uv[4][4];
; #pragma unroll
;                 for (int e = 0; e < 4; ++e) {
;                     float gg[4], ur[4], dr[4];
; #pragma unroll
;                     for (int m = 0; m < 4; ++m) { gg[m] = acc[ai][0][m][n][e] * rs[m] + bgn[e]; ur[m] = dpp_ror1(gg[m]); dr[m] = dpp_ror15(gg[m]); }
; #pragma unroll
;                     for (int m = 0; m < 4; ++m) {
;                         const float up = (fr == 0) ? (m > 0 ? ur[m > 0 ? m - 1 : 0] : xu[e]) : ur[m];
;                         const float dn = (fr == 15) ? (m < 3 ? dr[m < 3 ? m + 1 : 3] : xd[e]) : dr[m];
;                         const float c = w0[e] * up + w1[e] * gg[m] + w2[e] * dn + bb[e];
;                         uv[m][e] = silu_f(c) * (acc[ai][1][m][n][e] * rs[m] + bvn[e]);
;                     }
;                 }
; #pragma unroll
;                 for (int m = 0; m < 4; ++m) {
;                     u32x2 w; w.x = cvt_pk_bf16(uv[m][0], uv[m][1]); w.y = cvt_pk_bf16(uv[m][2], uv[m][3]);
;                     *(u32x2*)(U + (size_t)(u.pm * 256 + ai * 128 + wr * 64 + m * 16 + fr) * DFF + f0 + 4 * n) = w;
;                 }
;             }
	v_pk_add_f32 v[64:65], v[72:73], v[64:65]
	v_mov_b32_dpp v109, v56 row_ror:1 row_mask:0xf bank_mask:0xf
	v_mul_f32_e32 v98, 0xbfb8aa3b, v64
	v_mul_f32_e32 v99, 0xbfb8aa3b, v65
	v_exp_f32_e32 v98, v98
	v_exp_f32_e32 v99, v99
	v_mov_b32_dpp v111, v57 row_ror:1 row_mask:0xf bank_mask:0xf
	v_mov_b32_dpp v106, v66 row_ror:15 row_mask:0xf bank_mask:0xf
	v_add_f32_e32 v98, 1.0, v98
	v_add_f32_e32 v99, 1.0, v99
	v_rcp_f32_e32 v98, v98
	v_rcp_f32_e32 v99, v99
	v_mov_b32_dpp v108, v67 row_ror:15 row_mask:0xf bank_mask:0xf
	v_pk_fma_f32 v[96:97], v[66:67], v[82:83], v[96:97]
	v_mad_i64_i32 v[66:67], s[0:1], v100, s8, v[128:129]
	v_cndmask_b32_e64 v101, v111, v103, s[38:39]
	v_cndmask_b32_e64 v100, v109, v102, s[38:39]
	v_pk_mul_f32 v[100:101], v[76:77], v[100:101]
	v_pk_fma_f32 v[58:59], v[58:59], v[194:195], v[90:91] op_sel_hi:[1,0,1]
	v_pk_fma_f32 v[56:57], v[56:57], v[80:81], v[100:101]
	v_pk_fma_f32 v[60:61], v[60:61], v[188:189], v[84:85] op_sel_hi:[1,0,1]
	v_pk_mul_f32 v[64:65], v[64:65], v[98:99]
	v_mov_b32_dpp v101, v58 row_ror:15 row_mask:0xf bank_mask:0xf
	v_mov_b32_dpp v103, v59 row_ror:15 row_mask:0xf bank_mask:0xf
	v_pk_mul_f32 v[60:61], v[60:61], v[64:65]
	v_cndmask_b32_e64 v65, v108, v103, s[40:41]
	v_cndmask_b32_e64 v64, v106, v101, s[40:41]
	v_pk_fma_f32 v[64:65], v[70:71], v[64:65], v[96:97]
	v_cvt_pk_bf16_f32 v60, v60, v61
	v_pk_add_f32 v[64:65], v[74:75], v[64:65]
	v_pk_fma_f32 v[62:63], v[62:63], v[188:189], v[86:87] op_sel_hi:[1,0,1]
	v_mul_f32_e32 v61, 0xbfb8aa3b, v64
	v_exp_f32_e32 v61, v61
	v_lshl_add_u64 v[66:67], v[66:67], 0, v[130:131]
	v_add_f32_e32 v61, 1.0, v61
	v_rcp_f32_e32 v96, v61
	v_mul_f32_e32 v61, 0xbfb8aa3b, v65
	v_exp_f32_e32 v61, v61
	v_mov_b32_dpp v100, v58 row_ror:1 row_mask:0xf bank_mask:0xf
	v_mov_b32_dpp v102, v59 row_ror:1 row_mask:0xf bank_mask:0xf
	v_cndmask_b32_e64 v99, v102, v107, s[38:39]
	v_add_f32_e32 v61, 1.0, v61
	v_rcp_f32_e32 v97, v61
	v_cndmask_b32_e64 v98, v100, v105, s[38:39]
	v_pk_mul_f32 v[98:99], v[78:79], v[98:99]
	v_pk_fma_f32 v[52:53], v[52:53], v[194:195], v[84:85] op_sel_hi:[1,0,1]
	v_pk_mul_f32 v[64:65], v[64:65], v[96:97]
	v_pk_fma_f32 v[58:59], v[58:59], v[82:83], v[98:99]
	v_pk_mul_f32 v[62:63], v[62:63], v[64:65]
	v_cvt_pk_bf16_f32 v61, v62, v63
	global_store_dwordx2 v[66:67], v[60:61], off
	v_add_u32_e32 v60, 0x90, v187
	v_mad_i64_i32 v[60:61], s[0:1], v60, s8, v[128:129]
	v_lshl_add_u64 v[96:97], v[60:61], 0, v[130:131]
	v_pk_fma_f32 v[60:61], v[48:49], v[190:191], v[88:89] op_sel_hi:[1,0,1]
	s_nop 1
	v_mov_b32_dpp v98, v61 row_ror:1 row_mask:0xf bank_mask:0xf
	v_mov_b32_dpp v62, v60 row_ror:1 row_mask:0xf bank_mask:0xf
	v_pk_fma_f32 v[48:49], v[44:45], v[190:191], v[84:85] op_sel_hi:[1,0,1]
	v_cndmask_b32_e64 v45, v98, v111, s[38:39]
	v_cndmask_b32_e64 v44, v62, v109, s[38:39]
	v_mov_b32_dpp v63, v60 row_ror:15 row_mask:0xf bank_mask:0xf
	v_mov_b32_dpp v99, v61 row_ror:15 row_mask:0xf bank_mask:0xf
	v_pk_mul_f32 v[44:45], v[76:77], v[44:45]
	v_pk_fma_f32 v[50:51], v[50:51], v[190:191], v[90:91] op_sel_hi:[1,0,1]
	v_pk_fma_f32 v[60:61], v[60:61], v[80:81], v[44:45]
	v_cndmask_b32_e64 v45, v112, v99, s[40:41]
	v_cndmask_b32_e64 v44, v110, v63, s[40:41]
	v_pk_fma_f32 v[44:45], v[68:69], v[44:45], v[56:57]
	v_pk_add_f32 v[44:45], v[72:73], v[44:45]
	v_mul_f32_e32 v56, 0xbfb8aa3b, v44
	v_mul_f32_e32 v57, 0xbfb8aa3b, v45
	v_exp_f32_e32 v56, v56
	v_exp_f32_e32 v57, v57
	v_mov_b32_dpp v104, v50 row_ror:1 row_mask:0xf bank_mask:0xf
	v_mov_b32_dpp v106, v51 row_ror:1 row_mask:0xf bank_mask:0xf
	v_add_f32_e32 v56, 1.0, v56
	v_add_f32_e32 v57, 1.0, v57
	v_rcp_f32_e32 v56, v56
	v_rcp_f32_e32 v57, v57
	v_pk_fma_f32 v[54:55], v[54:55], v[194:195], v[86:87] op_sel_hi:[1,0,1]
	v_pk_mul_f32 v[44:45], v[44:45], v[56:57]
	v_mov_b32_dpp v105, v50 row_ror:15 row_mask:0xf bank_mask:0xf
	v_pk_mul_f32 v[44:45], v[52:53], v[44:45]
	v_mov_b32_dpp v107, v51 row_ror:15 row_mask:0xf bank_mask:0xf
	v_cvt_pk_bf16_f32 v52, v44, v45
	v_pk_fma_f32 v[44:45], v[46:47], v[190:191], v[86:87] op_sel_hi:[1,0,1]
	v_cndmask_b32_e64 v47, v106, v102, s[38:39]
	v_cndmask_b32_e64 v46, v104, v100, s[38:39]
	v_pk_mul_f32 v[46:47], v[78:79], v[46:47]
	v_pk_fma_f32 v[40:41], v[40:41], v[186:187], v[88:89] op_sel_hi:[1,0,1]
	v_pk_fma_f32 v[46:47], v[50:51], v[82:83], v[46:47]
	v_cndmask_b32_e64 v51, v103, v107, s[40:41]
	v_cndmask_b32_e64 v50, v101, v105, s[40:41]
	v_pk_fma_f32 v[50:51], v[70:71], v[50:51], v[58:59]
	v_pk_fma_f32 v[36:37], v[36:37], v[186:187], v[84:85] op_sel_hi:[1,0,1]
	v_pk_add_f32 v[50:51], v[74:75], v[50:51]
	v_pk_fma_f32 v[42:43], v[42:43], v[186:187], v[90:91] op_sel_hi:[1,0,1]
	v_mul_f32_e32 v53, 0xbfb8aa3b, v50
	v_exp_f32_e32 v53, v53
	v_pk_fma_f32 v[38:39], v[38:39], v[186:187], v[86:87] op_sel_hi:[1,0,1]
	v_mov_b32_e32 v85, v2
	v_mov_b32_e32 v84, v2
	v_add_f32_e32 v53, 1.0, v53
	v_rcp_f32_e32 v56, v53
	v_mul_f32_e32 v53, 0xbfb8aa3b, v51
	v_exp_f32_e32 v53, v53
	s_nop 0
	v_add_f32_e32 v53, 1.0, v53
	v_rcp_f32_e32 v57, v53
	s_nop 0
	v_pk_mul_f32 v[50:51], v[50:51], v[56:57]
	s_nop 0
	v_pk_mul_f32 v[50:51], v[54:55], v[50:51]
	v_cvt_pk_bf16_f32 v53, v50, v51
	v_add_u32_e32 v50, 0xa0, v187
	v_mad_i64_i32 v[50:51], s[0:1], v50, s8, v[128:129]
	v_lshl_add_u64 v[64:65], v[50:51], 0, v[130:131]
	v_mov_b32_dpp v50, v40 row_ror:1 row_mask:0xf bank_mask:0xf
	v_mov_b32_dpp v51, v41 row_ror:1 row_mask:0xf bank_mask:0xf
	v_cndmask_b32_e64 v51, v51, v98, s[38:39]
	v_cndmask_b32_e64 v50, v50, v62, s[38:39]
	v_mov_b32_dpp v54, v40 row_ror:15 row_mask:0xf bank_mask:0xf
	v_mov_b32_dpp v55, v41 row_ror:15 row_mask:0xf bank_mask:0xf
	v_pk_mul_f32 v[50:51], v[76:77], v[50:51]
	global_store_dwordx2 v[96:97], v[52:53], off
	s_waitcnt lgkmcnt(0)
; #define LAS __attribute__((address_space(3)))
; __device__ __forceinline__ float silu_f(float x) { return x * fast_rcp(1.0f + __expf(-x)); }
; __device__ __forceinline__ float dpp_ror1(float v)  { return __builtin_bit_cast(float, __builtin_amdgcn_update_dpp(0, __builtin_bit_cast(int, v), 0x121, 0xf, 0xf, false)); }
; __device__ __forceinline__ float dpp_ror15(float v) { return __builtin_bit_cast(float, __builtin_amdgcn_update_dpp(0, __builtin_bit_cast(int, v), 0x12F, 0xf, 0xf, false)); }
;     __device__ __forceinline__ void operator()(const pg8::f32x4 (&acc)[2][2][4][2], const pg8::Unit& u, int wr, int wc, int fr, int fq) const {
;     ...
;                 const f32x4 w0 = *(const f32x4*)(cw + f0 + 4 * n), w1 = *(const f32x4*)(cw + DFF + f0 + 4 * n), w2 = *(const f32x4*)(cw + 2 * DFF + f0 + 4 * n), bb = *(const f32x4*)(cb + f0 + 4 * n);
;                 const f32x4 xu = *(const LAS f32x4*)(xg + (giu * 2 + 1) * 128 + lf + 4 * n), xd = *(const LAS f32x4*)(xg + (gid * 2 + 0) * 128 + lf + 4 * n);
;                 float uv[4][4];
; #pragma unroll
;                 for (int e = 0; e < 4; ++e) {
;                     float gg[4], ur[4], dr[4];
; #pragma unroll
;                     for (int m = 0; m < 4; ++m) { gg[m] = acc[ai][0][m][n][e] * rs[m] + bgn[e]; ur[m] = dpp_ror1(gg[m]); dr[m] = dpp_ror15(gg[m]); }
; #pragma unroll
;                     for (int m = 0; m < 4; ++m) {
;                         const float up = (fr == 0) ? (m > 0 ? ur[m > 0 ? m - 1 : 0] : xu[e]) : ur[m];
;                         const float dn = (fr == 15) ? (m < 3 ? dr[m < 3 ? m + 1 : 3] : xd[e]) : dr[m];
;                         const float c = w0[e] * up + w1[e] * gg[m] + w2[e] * dn + bb[e];
;                         uv[m][e] = silu_f(c) * (acc[ai][1][m][n][e] * rs[m] + bvn[e]);
;                     }
;                 }
; #pragma unroll
;                 for (int m = 0; m < 4; ++m) {
;                     u32x2 w; w.x = cvt_pk_bf16(uv[m][0], uv[m][1]); w.y = cvt_pk_bf16(uv[m][2], uv[m][3]);
;                     *(u32x2*)(U + (size_t)(u.pm * 256 + ai * 128 + wr * 64 + m * 16 + fr) * DFF + f0 + 4 * n) = w;
;                 }
;             }
	v_cndmask_b32_e64 v53, v55, v93, s[40:41]
	v_cndmask_b32_e64 v52, v54, v92, s[40:41]
	v_pk_fma_f32 v[40:41], v[40:41], v[80:81], v[50:51]
	v_mov_b32_e32 v76, v2
	v_pk_fma_f32 v[40:41], v[68:69], v[52:53], v[40:41]
	v_pk_add_f32 v[40:41], v[72:73], v[40:41]
	v_mov_b32_e32 v80, v2
	v_mul_f32_e32 v50, 0xbfb8aa3b, v40
	v_mul_f32_e32 v51, 0xbfb8aa3b, v41
	v_exp_f32_e32 v50, v50
	v_exp_f32_e32 v51, v51
	v_mov_b32_dpp v52, v43 row_ror:15 row_mask:0xf bank_mask:0xf
	v_mov_b32_e32 v77, v2
	v_add_f32_e32 v50, 1.0, v50
	v_add_f32_e32 v51, 1.0, v51
	v_rcp_f32_e32 v50, v50
	v_rcp_f32_e32 v51, v51
	v_mov_b32_e32 v81, v2
	v_pk_mul_f32 v[40:41], v[40:41], v[50:51]
	s_nop 0
	v_pk_mul_f32 v[36:37], v[36:37], v[40:41]
	v_cndmask_b32_e64 v41, v99, v55, s[40:41]
	v_cndmask_b32_e64 v40, v63, v54, s[40:41]
	v_pk_fma_f32 v[40:41], v[68:69], v[40:41], v[60:61]
	v_cvt_pk_bf16_f32 v36, v36, v37
	v_pk_add_f32 v[40:41], v[72:73], v[40:41]
	v_mul_f32_e32 v50, 0xbfb8aa3b, v40
	v_mul_f32_e32 v51, 0xbfb8aa3b, v41
	v_exp_f32_e32 v50, v50
	v_exp_f32_e32 v51, v51
	v_mov_b32_dpp v37, v42 row_ror:1 row_mask:0xf bank_mask:0xf
	v_add_f32_e32 v50, 1.0, v50
	v_add_f32_e32 v51, 1.0, v51
	v_rcp_f32_e32 v50, v50
	v_rcp_f32_e32 v51, v51
	s_nop 0
	v_pk_mul_f32 v[40:41], v[40:41], v[50:51]
	s_nop 0
	v_pk_mul_f32 v[40:41], v[48:49], v[40:41]
	v_cvt_pk_bf16_f32 v40, v40, v41
	v_mov_b32_dpp v48, v43 row_ror:1 row_mask:0xf bank_mask:0xf
	v_cndmask_b32_e64 v49, v48, v106, s[38:39]
	v_cndmask_b32_e64 v48, v37, v104, s[38:39]
	v_mov_b32_dpp v41, v42 row_ror:15 row_mask:0xf bank_mask:0xf
	v_pk_mul_f32 v[48:49], v[78:79], v[48:49]
	v_cndmask_b32_e64 v51, v52, v95, s[40:41]
	v_cndmask_b32_e64 v50, v41, v94, s[40:41]
	v_pk_fma_f32 v[42:43], v[42:43], v[82:83], v[48:49]
	v_mov_b32_e32 v78, v2
	v_pk_fma_f32 v[42:43], v[70:71], v[50:51], v[42:43]
	v_mov_b32_e32 v83, v2
	v_pk_add_f32 v[42:43], v[74:75], v[42:43]
	v_mov_b32_e32 v79, v2
	v_mul_f32_e32 v37, 0xbfb8aa3b, v42
	v_exp_f32_e32 v37, v37
	v_mov_b32_e32 v82, v2
	v_add_f32_e32 v37, 1.0, v37
	v_rcp_f32_e32 v48, v37
	v_mul_f32_e32 v37, 0xbfb8aa3b, v43
	v_exp_f32_e32 v37, v37
	s_nop 0
	v_add_f32_e32 v37, 1.0, v37
	v_rcp_f32_e32 v49, v37
	s_nop 0
	v_pk_mul_f32 v[42:43], v[42:43], v[48:49]
	s_nop 0
	v_pk_mul_f32 v[38:39], v[38:39], v[42:43]
	v_cndmask_b32_e64 v43, v107, v52, s[40:41]
	v_cndmask_b32_e64 v42, v105, v41, s[40:41]
	v_pk_fma_f32 v[42:43], v[70:71], v[42:43], v[46:47]
	s_nop 0
	v_pk_add_f32 v[42:43], v[74:75], v[42:43]
	v_mul_f32_e32 v37, 0xbfb8aa3b, v42
	v_exp_f32_e32 v37, v37
	s_nop 0
	v_add_f32_e32 v37, 1.0, v37
	v_rcp_f32_e32 v46, v37
	v_mul_f32_e32 v37, 0xbfb8aa3b, v43
	v_exp_f32_e32 v37, v37
	s_nop 0
	v_add_f32_e32 v37, 1.0, v37
	v_rcp_f32_e32 v47, v37
	v_cvt_pk_bf16_f32 v37, v38, v39
	v_add_u32_e32 v38, 0xb0, v187
	v_mad_i64_i32 v[38:39], s[0:1], v38, s8, v[128:129]
	v_pk_mul_f32 v[42:43], v[42:43], v[46:47]
	v_lshl_add_u64 v[68:69], v[38:39], 0, v[130:131]
	v_pk_mul_f32 v[42:43], v[44:45], v[42:43]
	global_store_dwordx2 v[68:69], v[36:37], off
	v_cvt_pk_bf16_f32 v41, v42, v43
	global_store_dwordx2 v[64:65], v[40:41], off
	global_load_dwordx4 v[60:63], v[192:193], off offset:16
	global_load_dwordx4 v[52:55], v[192:193], off offset:528
	global_load_dwordx4 v[44:47], v[196:197], off offset:16
	global_load_dwordx4 v[48:51], v[132:133], off offset:3088
	global_load_dwordx4 v[36:39], v[134:135], off offset:2064
	global_load_dwordx4 v[40:43], v[198:199], off offset:16
	ds_read_b128 v[70:73], v226
	ds_read_b128 v[56:59], v225 offset:1040
	s_mov_b64 s[0:1], -1
	s_waitcnt vmcnt(5)
	v_pk_fma_f32 v[28:29], v[28:29], v[188:189], v[60:61] op_sel_hi:[1,0,1]
	s_nop 1
	v_mov_b32_dpp v74, v28 row_ror:1 row_mask:0xf bank_mask:0xf
	v_mov_b32_dpp v76, v29 row_ror:1 row_mask:0xf bank_mask:0xf
	s_waitcnt lgkmcnt(1)
	v_cndmask_b32_e64 v71, v76, v71, s[38:39]
	v_cndmask_b32_e64 v70, v74, v70, s[38:39]
	v_pk_fma_f32 v[30:31], v[30:31], v[188:189], v[62:63] op_sel_hi:[1,0,1]
	s_waitcnt vmcnt(3)
	v_pk_mul_f32 v[70:71], v[44:45], v[70:71]
	v_mov_b32_dpp v75, v28 row_ror:15 row_mask:0xf bank_mask:0xf
	v_mov_b32_dpp v78, v30 row_ror:1 row_mask:0xf bank_mask:0xf
	v_mov_b32_dpp v80, v31 row_ror:1 row_mask:0xf bank_mask:0xf
	v_mov_b32_dpp v77, v29 row_ror:15 row_mask:0xf bank_mask:0xf
	s_waitcnt vmcnt(2)
	v_pk_fma_f32 v[28:29], v[28:29], v[48:49], v[70:71]
	v_cndmask_b32_e64 v71, v80, v73, s[38:39]
	v_cndmask_b32_e64 v70, v78, v72, s[38:39]
	v_pk_fma_f32 v[24:25], v[24:25], v[194:195], v[60:61] op_sel_hi:[1,0,1]
	v_pk_mul_f32 v[70:71], v[46:47], v[70:71]
	v_mov_b32_dpp v79, v30 row_ror:15 row_mask:0xf bank_mask:0xf
	v_mov_b32_dpp v83, v24 row_ror:15 row_mask:0xf bank_mask:0xf
	v_mov_b32_dpp v85, v25 row_ror:15 row_mask:0xf bank_mask:0xf
	v_mov_b32_dpp v81, v31 row_ror:15 row_mask:0xf bank_mask:0xf
	v_pk_fma_f32 v[30:31], v[30:31], v[50:51], v[70:71]
	v_cndmask_b32_e64 v71, v77, v85, s[40:41]
	v_cndmask_b32_e64 v70, v75, v83, s[40:41]
	s_waitcnt vmcnt(1)
	v_pk_fma_f32 v[28:29], v[36:37], v[70:71], v[28:29]
	v_mov_b32_dpp v82, v24 row_ror:1 row_mask:0xf bank_mask:0xf
	s_waitcnt vmcnt(0)
; #define LAS __attribute__((address_space(3)))
; __device__ __forceinline__ float silu_f(float x) { return x * fast_rcp(1.0f + __expf(-x)); }
; __device__ __forceinline__ float dpp_ror1(float v)  { return __builtin_bit_cast(float, __builtin_amdgcn_update_dpp(0, __builtin_bit_cast(int, v), 0x121, 0xf, 0xf, false)); }
; __device__ __forceinline__ float dpp_ror15(float v) { return __builtin_bit_cast(float, __builtin_amdgcn_update_dpp(0, __builtin_bit_cast(int, v), 0x12F, 0xf, 0xf, false)); }
;     __device__ __forceinline__ void operator()(const pg8::f32x4 (&acc)[2][2][4][2], const pg8::Unit& u, int wr, int wc, int fr, int fq) const {
;     ...
;                 const f32x4 w0 = *(const f32x4*)(cw + f0 + 4 * n), w1 = *(const f32x4*)(cw + DFF + f0 + 4 * n), w2 = *(const f32x4*)(cw + 2 * DFF + f0 + 4 * n), bb = *(const f32x4*)(cb + f0 + 4 * n);
;                 const f32x4 xu = *(const LAS f32x4*)(xg + (giu * 2 + 1) * 128 + lf + 4 * n), xd = *(const LAS f32x4*)(xg + (gid * 2 + 0) * 128 + lf + 4 * n);
;                 float uv[4][4];
; #pragma unroll
;                 for (int e = 0; e < 4; ++e) {
;                     float gg[4], ur[4], dr[4];
; #pragma unroll
;                     for (int m = 0; m < 4; ++m) { gg[m] = acc[ai][0][m][n][e] * rs[m] + bgn[e]; ur[m] = dpp_ror1(gg[m]); dr[m] = dpp_ror15(gg[m]); }
; #pragma unroll
;                     for (int m = 0; m < 4; ++m) {
;                         const float up = (fr == 0) ? (m > 0 ? ur[m > 0 ? m - 1 : 0] : xu[e]) : ur[m];
;                         const float dn = (fr == 15) ? (m < 3 ? dr[m < 3 ? m + 1 : 3] : xd[e]) : dr[m];
;                         const float c = w0[e] * up + w1[e] * gg[m] + w2[e] * dn + bb[e];
;                         uv[m][e] = silu_f(c) * (acc[ai][1][m][n][e] * rs[m] + bvn[e]);
;                     }
;                 }
; #pragma unroll
;                 for (int m = 0; m < 4; ++m) {
;                     u32x2 w; w.x = cvt_pk_bf16(uv[m][0], uv[m][1]); w.y = cvt_pk_bf16(uv[m][2], uv[m][3]);
;                     *(u32x2*)(U + (size_t)(u.pm * 256 + ai * 128 + wr * 64 + m * 16 + fr) * DFF + f0 + 4 * n) = w;
;                 }
;             }
	v_pk_add_f32 v[28:29], v[40:41], v[28:29]
	v_mov_b32_dpp v84, v25 row_ror:1 row_mask:0xf bank_mask:0xf
	v_mul_f32_e32 v70, 0xbfb8aa3b, v29
	v_exp_f32_e32 v70, v70
	v_cndmask_b32_e64 v73, v84, v76, s[38:39]
	v_cndmask_b32_e64 v72, v82, v74, s[38:39]
	v_pk_mul_f32 v[72:73], v[44:45], v[72:73]
	v_add_f32_e32 v70, 1.0, v70
	v_rcp_f32_e32 v71, v70
	v_mul_f32_e32 v70, 0xbfb8aa3b, v28
	v_exp_f32_e32 v70, v70
	v_pk_fma_f32 v[24:25], v[24:25], v[48:49], v[72:73]
	v_pk_fma_f32 v[26:27], v[26:27], v[194:195], v[62:63] op_sel_hi:[1,0,1]
	v_add_f32_e32 v70, 1.0, v70
	v_rcp_f32_e32 v70, v70
	v_pk_fma_f32 v[32:33], v[32:33], v[188:189], v[52:53] op_sel_hi:[1,0,1]
	v_mov_b32_dpp v73, v26 row_ror:15 row_mask:0xf bank_mask:0xf
	v_pk_mul_f32 v[28:29], v[28:29], v[70:71]
	v_mov_b32_dpp v75, v27 row_ror:15 row_mask:0xf bank_mask:0xf
	v_pk_mul_f32 v[28:29], v[32:33], v[28:29]
	v_cndmask_b32_e64 v33, v81, v75, s[40:41]
	v_cndmask_b32_e64 v32, v79, v73, s[40:41]
	v_pk_fma_f32 v[30:31], v[38:39], v[32:33], v[30:31]
	v_cvt_pk_bf16_f32 v28, v28, v29
	v_pk_add_f32 v[30:31], v[42:43], v[30:31]
	v_pk_fma_f32 v[34:35], v[34:35], v[188:189], v[54:55] op_sel_hi:[1,0,1]
	v_mul_f32_e32 v29, 0xbfb8aa3b, v31
	v_exp_f32_e32 v29, v29
	v_pk_fma_f32 v[20:21], v[20:21], v[194:195], v[52:53] op_sel_hi:[1,0,1]
	v_add_f32_e32 v29, 1.0, v29
	v_rcp_f32_e32 v33, v29
	v_mul_f32_e32 v29, 0xbfb8aa3b, v30
	v_exp_f32_e32 v29, v29
	v_pk_fma_f32 v[18:19], v[18:19], v[190:191], v[62:63] op_sel_hi:[1,0,1]
	v_mov_b32_dpp v72, v26 row_ror:1 row_mask:0xf bank_mask:0xf
	v_mov_b32_dpp v74, v27 row_ror:1 row_mask:0xf bank_mask:0xf
	v_add_f32_e32 v29, 1.0, v29
	v_rcp_f32_e32 v32, v29
	v_cndmask_b32_e64 v71, v74, v80, s[38:39]
	v_cndmask_b32_e64 v70, v72, v78, s[38:39]
	v_pk_mul_f32 v[70:71], v[46:47], v[70:71]
	v_pk_mul_f32 v[30:31], v[30:31], v[32:33]
	v_pk_mul_f32 v[30:31], v[34:35], v[30:31]
	v_cvt_pk_bf16_f32 v29, v30, v31
	global_store_dwordx2 v[66:67], v[28:29], off offset:8
	v_pk_fma_f32 v[28:29], v[16:17], v[190:191], v[60:61] op_sel_hi:[1,0,1]
	s_nop 1
	v_mov_b32_dpp v32, v29 row_ror:1 row_mask:0xf bank_mask:0xf
	v_mov_b32_dpp v30, v28 row_ror:1 row_mask:0xf bank_mask:0xf
	v_pk_fma_f32 v[16:17], v[12:13], v[190:191], v[52:53] op_sel_hi:[1,0,1]
	v_cndmask_b32_e64 v13, v32, v84, s[38:39]
	v_cndmask_b32_e64 v12, v30, v82, s[38:39]
	v_mov_b32_dpp v31, v28 row_ror:15 row_mask:0xf bank_mask:0xf
	v_mov_b32_dpp v33, v29 row_ror:15 row_mask:0xf bank_mask:0xf
	v_pk_mul_f32 v[12:13], v[44:45], v[12:13]
	v_pk_fma_f32 v[28:29], v[28:29], v[48:49], v[12:13]
	v_cndmask_b32_e64 v13, v85, v33, s[40:41]
	v_cndmask_b32_e64 v12, v83, v31, s[40:41]
	v_pk_fma_f32 v[12:13], v[36:37], v[12:13], v[24:25]
	v_pk_add_f32 v[12:13], v[40:41], v[12:13]
	v_mov_b32_dpp v34, v18 row_ror:1 row_mask:0xf bank_mask:0xf
	v_mul_f32_e32 v24, 0xbfb8aa3b, v13
	v_exp_f32_e32 v24, v24
	v_mov_b32_dpp v66, v19 row_ror:1 row_mask:0xf bank_mask:0xf
	v_add_f32_e32 v24, 1.0, v24
	v_rcp_f32_e32 v25, v24
	v_mul_f32_e32 v24, 0xbfb8aa3b, v12
	v_exp_f32_e32 v24, v24
	v_mov_b32_dpp v35, v18 row_ror:15 row_mask:0xf bank_mask:0xf
	v_mov_b32_dpp v67, v19 row_ror:15 row_mask:0xf bank_mask:0xf
	v_pk_fma_f32 v[26:27], v[26:27], v[50:51], v[70:71]
	v_add_f32_e32 v24, 1.0, v24
	v_rcp_f32_e32 v24, v24
	v_pk_fma_f32 v[22:23], v[22:23], v[194:195], v[54:55] op_sel_hi:[1,0,1]
	v_pk_fma_f32 v[4:5], v[4:5], v[186:187], v[60:61] op_sel_hi:[1,0,1]
	v_pk_fma_f32 v[8:9], v[8:9], v[186:187], v[52:53] op_sel_hi:[1,0,1]
	v_pk_mul_f32 v[12:13], v[12:13], v[24:25]
	v_pk_fma_f32 v[6:7], v[6:7], v[186:187], v[62:63] op_sel_hi:[1,0,1]
	v_pk_mul_f32 v[12:13], v[20:21], v[12:13]
	v_pk_fma_f32 v[10:11], v[10:11], v[186:187], v[54:55] op_sel_hi:[1,0,1]
	v_cvt_pk_bf16_f32 v20, v12, v13
	v_pk_fma_f32 v[12:13], v[14:15], v[190:191], v[54:55] op_sel_hi:[1,0,1]
	v_cndmask_b32_e64 v15, v66, v74, s[38:39]
	v_cndmask_b32_e64 v14, v34, v72, s[38:39]
	v_pk_mul_f32 v[14:15], v[46:47], v[14:15]
	s_nop 0
	v_pk_fma_f32 v[14:15], v[18:19], v[50:51], v[14:15]
	v_cndmask_b32_e64 v19, v75, v67, s[40:41]
	v_cndmask_b32_e64 v18, v73, v35, s[40:41]
	v_pk_fma_f32 v[18:19], v[38:39], v[18:19], v[26:27]
	s_nop 0
	v_pk_add_f32 v[18:19], v[42:43], v[18:19]
	s_nop 0
	v_mul_f32_e32 v21, 0xbfb8aa3b, v19
	v_exp_f32_e32 v21, v21
	s_nop 0
	v_add_f32_e32 v21, 1.0, v21
	v_rcp_f32_e32 v25, v21
	v_mul_f32_e32 v21, 0xbfb8aa3b, v18
	v_exp_f32_e32 v21, v21
	s_nop 0
	v_add_f32_e32 v21, 1.0, v21
	v_rcp_f32_e32 v24, v21
	s_nop 0
	v_pk_mul_f32 v[18:19], v[18:19], v[24:25]
	s_nop 0
	v_pk_mul_f32 v[18:19], v[22:23], v[18:19]
	v_cvt_pk_bf16_f32 v21, v18, v19
	v_mov_b32_dpp v18, v4 row_ror:1 row_mask:0xf bank_mask:0xf
	v_mov_b32_dpp v19, v5 row_ror:1 row_mask:0xf bank_mask:0xf
	v_cndmask_b32_e64 v19, v19, v32, s[38:39]
	v_cndmask_b32_e64 v18, v18, v30, s[38:39]
	v_mov_b32_dpp v22, v4 row_ror:15 row_mask:0xf bank_mask:0xf
	v_mov_b32_dpp v23, v5 row_ror:15 row_mask:0xf bank_mask:0xf
	v_pk_mul_f32 v[18:19], v[44:45], v[18:19]
	global_store_dwordx2 v[96:97], v[20:21], off offset:8
	s_waitcnt lgkmcnt(0)
; #define PG8_BAR __builtin_amdgcn_s_barrier()
; __device__ __forceinline__ float silu_f(float x) { return x * fast_rcp(1.0f + __expf(-x)); }
; template <class Epi, class Sched, bool ALIGN_EPI = false, bool SP2 = false>
; __device__ __forceinline__ void gemm_phase(PG8_LAS unsigned char* lds, const Gemm g, const Sched& S, const Epi& E) {
;     ...
;         if constexpr (ALIGN_EPI) { if (wr == 0) PG8_BAR; }
;         if constexpr (!Epi::AFTER_DRAIN) { E(acc, cur, wr, wc, fr, fq); S.done(cur); }
;         if (!has_next) break;
; #pragma unroll
;         for (int a = 0; a < 2; ++a)
; #pragma unroll
;             for (int b = 0; b < 2; ++b)
; #pragma unroll
;                 for (int m = 0; m < 4; ++m)
; #pragma unroll
;                     for (int n = 0; n < 2; ++n) acc[a][b][m][n] = (f32x4){0.f, 0.f, 0.f, 0.f};
;         cur = nxt; cA = nA; cB = nB; ++ui;
;         if constexpr (ALIGN_EPI) { if (wr == 1) PG8_BAR; }
;     __device__ __forceinline__ void operator()(const pg8::f32x4 (&acc)[2][2][4][2], const pg8::Unit& u, int wr, int wc, int fr, int fq) const {
;     ...
;                     for (int m = 0; m < 4; ++m) {
;                         const float up = (fr == 0) ? (m > 0 ? ur[m > 0 ? m - 1 : 0] : xu[e]) : ur[m];
;                         const float dn = (fr == 15) ? (m < 3 ? dr[m < 3 ? m + 1 : 3] : xd[e]) : dr[m];
;                         const float c = w0[e] * up + w1[e] * gg[m] + w2[e] * dn + bb[e];
;                         uv[m][e] = silu_f(c) * (acc[ai][1][m][n][e] * rs[m] + bvn[e]);
;                     }
;                 }
; #pragma unroll
;                 for (int m = 0; m < 4; ++m) {
;                     u32x2 w; w.x = cvt_pk_bf16(uv[m][0], uv[m][1]); w.y = cvt_pk_bf16(uv[m][2], uv[m][3]);
;                     *(u32x2*)(U + (size_t)(u.pm * 256 + ai * 128 + wr * 64 + m * 16 + fr) * DFF + f0 + 4 * n) = w;
;                 }
;             }
	v_cndmask_b32_e64 v21, v23, v57, s[40:41]
	v_cndmask_b32_e64 v20, v22, v56, s[40:41]
	v_pk_fma_f32 v[4:5], v[4:5], v[48:49], v[18:19]
	s_nop 0
	v_pk_fma_f32 v[4:5], v[36:37], v[20:21], v[4:5]
	v_pk_add_f32 v[4:5], v[40:41], v[4:5]
	s_nop 0
	v_mul_f32_e32 v18, 0xbfb8aa3b, v5
	v_exp_f32_e32 v18, v18
	v_mov_b32_dpp v20, v7 row_ror:15 row_mask:0xf bank_mask:0xf
	v_add_f32_e32 v18, 1.0, v18
	v_rcp_f32_e32 v19, v18
	v_mul_f32_e32 v18, 0xbfb8aa3b, v4
	v_exp_f32_e32 v18, v18
	s_nop 0
	v_add_f32_e32 v18, 1.0, v18
	v_rcp_f32_e32 v18, v18
	s_nop 0
	v_pk_mul_f32 v[4:5], v[4:5], v[18:19]
	s_nop 0
	v_pk_mul_f32 v[4:5], v[8:9], v[4:5]
	v_cndmask_b32_e64 v9, v33, v23, s[40:41]
	v_cndmask_b32_e64 v8, v31, v22, s[40:41]
	v_pk_fma_f32 v[8:9], v[36:37], v[8:9], v[28:29]
	v_cvt_pk_bf16_f32 v4, v4, v5
	v_pk_add_f32 v[8:9], v[40:41], v[8:9]
	v_mul_f32_e32 v18, 0xbfb8aa3b, v9
	v_exp_f32_e32 v18, v18
	v_mov_b32_dpp v5, v6 row_ror:1 row_mask:0xf bank_mask:0xf
	v_add_f32_e32 v18, 1.0, v18
	v_rcp_f32_e32 v19, v18
	v_mul_f32_e32 v18, 0xbfb8aa3b, v8
	v_exp_f32_e32 v18, v18
	s_nop 0
	v_add_f32_e32 v18, 1.0, v18
	v_rcp_f32_e32 v18, v18
	s_nop 0
	v_pk_mul_f32 v[8:9], v[8:9], v[18:19]
	s_nop 0
	v_pk_mul_f32 v[8:9], v[16:17], v[8:9]
	v_cvt_pk_bf16_f32 v8, v8, v9
	v_mov_b32_dpp v16, v7 row_ror:1 row_mask:0xf bank_mask:0xf
	v_cndmask_b32_e64 v17, v16, v66, s[38:39]
	v_cndmask_b32_e64 v16, v5, v34, s[38:39]
	v_mov_b32_dpp v9, v6 row_ror:15 row_mask:0xf bank_mask:0xf
	v_pk_mul_f32 v[16:17], v[46:47], v[16:17]
	v_cndmask_b32_e64 v19, v20, v59, s[40:41]
	v_cndmask_b32_e64 v18, v9, v58, s[40:41]
	v_pk_fma_f32 v[6:7], v[6:7], v[50:51], v[16:17]
	s_nop 0
	v_pk_fma_f32 v[6:7], v[38:39], v[18:19], v[6:7]
	s_nop 0
	v_pk_add_f32 v[6:7], v[42:43], v[6:7]
	s_nop 0
	v_mul_f32_e32 v5, 0xbfb8aa3b, v6
	v_exp_f32_e32 v5, v5
	s_nop 0
	v_add_f32_e32 v5, 1.0, v5
	v_rcp_f32_e32 v16, v5
	v_mul_f32_e32 v5, 0xbfb8aa3b, v7
	v_exp_f32_e32 v5, v5
	s_nop 0
	v_add_f32_e32 v5, 1.0, v5
	v_rcp_f32_e32 v17, v5
	s_nop 0
	v_pk_mul_f32 v[6:7], v[6:7], v[16:17]
	s_nop 0
	v_pk_mul_f32 v[6:7], v[10:11], v[6:7]
	v_cndmask_b32_e64 v11, v67, v20, s[40:41]
	v_cndmask_b32_e64 v10, v35, v9, s[40:41]
	v_pk_fma_f32 v[10:11], v[38:39], v[10:11], v[14:15]
	s_nop 0
	v_pk_add_f32 v[10:11], v[42:43], v[10:11]
	s_nop 0
	v_mul_f32_e32 v5, 0xbfb8aa3b, v11
	v_exp_f32_e32 v5, v5
	s_nop 0
	v_add_f32_e32 v5, 1.0, v5
	v_rcp_f32_e32 v15, v5
	v_mul_f32_e32 v5, 0xbfb8aa3b, v10
	v_exp_f32_e32 v5, v5
	s_nop 0
	v_add_f32_e32 v5, 1.0, v5
	v_rcp_f32_e32 v14, v5
	v_cvt_pk_bf16_f32 v5, v6, v7
	global_store_dwordx2 v[68:69], v[4:5], off offset:8
	v_pk_mul_f32 v[10:11], v[10:11], v[14:15]
	s_nop 0
	v_pk_mul_f32 v[10:11], v[12:13], v[10:11]
	s_nop 0
	v_cvt_pk_bf16_f32 v9, v10, v11
	global_store_dwordx2 v[64:65], v[8:9], off offset:8
	s_cbranch_vccnz .LBB0_332
	s_andn2_b64 vcc, exec, s[56:57]
	s_cbranch_vccnz .LBB0_331
	s_barrier
	s_branch .LBB0_331
